# adds: ssd prologue issues first B/x^T block loads after the state fragments landed; per-block scalar table loads batched
# speedup vs baseline: 1.0466x; 1.0059x over previous
.LBB0_199:
	s_cmpk_gt_i32 s16, 0x3ff
	s_mov_b64 s[0:1], -1
	s_cbranch_scc0 .LBB0_221
	s_add_i32 s8, s16, 0xfffffc00
	s_and_b32 s9, s16, 3
	s_bfe_i32 s12, s16, 0x10008
	v_mov_b32_e32 v176, v167
	s_lshr_b32 s11, s8, 2
	s_and_b32 s12, s12, 3
	s_lshl_b32 s17, s9, 9
	v_readfirstlane_b32 s20, v176
	v_ashrrev_i32_e32 v169, 3, v176
	s_xor_b32 s13, s12, s11
	s_ashr_i32 s11, s20, 6
	s_lshr_b32 s19, s8, 4
	s_lshl_b32 s8, s9, 3
	v_add_u32_e32 v10, s17, v169
	v_mov_b64_e32 v[8:9], s[82:83]
	s_add_i32 s34, s11, s8
	v_lshlrev_b32_e32 v0, 3, v176
	s_lshl_b32 s12, s9, 7
	s_lshl_b32 s28, s9, 8
	v_mad_i64_i32 v[8:9], s[8:9], v10, s37, v[8:9]
	v_and_b32_e32 v166, 56, v0
	s_lshl_b32 s8, s19, 9
	s_mov_b32 s9, s29
	v_lshl_add_u64 v[8:9], v[8:9], 0, s[8:9]
	v_lshlrev_b32_e32 v10, 1, v166
	v_mov_b32_e32 v11, v157
	v_lshl_add_u64 v[32:33], v[8:9], 0, v[10:11]
	s_mov_b32 s8, 0x102000
	v_add_co_u32_e32 v12, vcc, s8, v32
	s_mov_b32 s8, 0x204000
	s_nop 0
	v_addc_co_u32_e32 v13, vcc, 0, v33, vcc
	v_add_co_u32_e32 v16, vcc, s8, v32
	s_mov_b32 s8, 0x306000
	s_nop 0
	v_addc_co_u32_e32 v17, vcc, 0, v33, vcc
	v_add_co_u32_e32 v20, vcc, s8, v32
	s_mov_b32 s8, 0x408000
	s_nop 0
	v_addc_co_u32_e32 v21, vcc, 0, v33, vcc
	v_add_co_u32_e32 v24, vcc, s8, v32
	s_mov_b32 s8, 0x50a000
	s_nop 0
	v_addc_co_u32_e32 v25, vcc, 0, v33, vcc
	v_add_co_u32_e32 v28, vcc, s8, v32
	s_mov_b32 s8, 0x60c000
	s_nop 0
	v_addc_co_u32_e32 v29, vcc, 0, v33, vcc
	v_add_co_u32_e32 v34, vcc, s8, v32
	s_mov_b32 s8, 0x70e000
	s_nop 0
	v_addc_co_u32_e32 v35, vcc, 0, v33, vcc
	v_add_co_u32_e32 v36, vcc, s8, v32
	s_lshl_b32 s8, s34, 5
	s_add_i32 s8, s8, s19
	s_lshl_b32 s0, s14, 4
	s_and_b32 s10, s15, 3
	s_ashr_i32 s9, s8, 31
	s_and_b32 s0, s0, 0xffffff00
	s_lshl_b32 s1, s10, 16
	s_and_b32 s18, s13, 3
	s_lshl_b64 s[8:9], s[8:9], 14
	v_readlane_b32 s24, v251, 49
	v_and_b32_e32 v171, 15, v176
	v_readlane_b32 s25, v251, 50
	s_add_u32 s8, s24, s8
	v_ashrrev_i32_e32 v177, 4, v176
	s_addc_u32 s9, s25, s9
	v_lshlrev_b32_e32 v40, 8, v171
	v_mov_b32_e32 v41, v157
	v_and_b32_e32 v168, 0x78, v0
	v_lshl_add_u32 v0, s19, 8, v177
	v_lshl_add_u64 v[40:41], s[8:9], 0, v[40:41]
	v_and_b32_e32 v80, 48, v176
	v_mov_b32_e32 v81, v157
	s_lshl_b32 s19, s13, 6
	v_addc_co_u32_e32 v37, vcc, 0, v33, vcc
	v_lshl_add_u64 v[40:41], v[40:41], 0, v[80:81]
	s_movk_i32 s8, 0x2000
	v_add_u32_e32 v42, s19, v177
	s_waitcnt lgkmcnt(0)
	v_ashrrev_i32_e32 v1, 31, v0
	v_add_co_u32_e32 v60, vcc, s8, v40
	v_ashrrev_i32_e32 v43, 31, v42
	v_lshlrev_b64 v[2:3], 10, v[0:1]
	v_add_u32_e32 v0, 32, v0
	v_addc_co_u32_e32 v61, vcc, 0, v41, vcc
	s_movk_i32 s8, 0x3000
	v_lshlrev_b64 v[52:53], 10, v[42:43]
	v_add_u32_e32 v42, 32, v42
	v_readlane_b32 s22, v251, 30
	v_ashrrev_i32_e32 v1, 31, v0
	v_add_co_u32_e32 v86, vcc, s8, v40
	v_readlane_b32 s8, v251, 28
	v_ashrrev_i32_e32 v43, 31, v42
	v_readlane_b32 s23, v251, 31
	v_lshlrev_b64 v[0:1], 10, v[0:1]
	v_readlane_b32 s9, v251, 29
	v_lshlrev_b64 v[42:43], 10, v[42:43]
	v_lshl_add_u64 v[2:3], s[22:23], 0, v[2:3]
	v_lshl_add_u64 v[0:1], s[22:23], 0, v[0:1]
	v_addc_co_u32_e32 v87, vcc, 0, v41, vcc
	v_lshl_add_u64 v[52:53], s[8:9], 0, v[52:53]
	v_lshl_add_u64 v[42:43], s[8:9], 0, v[42:43]
	s_movk_i32 s8, 0x1000
	v_lshl_add_u64 v[2:3], v[2:3], 0, s[28:29]
	v_lshlrev_b32_e32 v156, 1, v168
	v_lshl_add_u64 v[0:1], v[0:1], 0, s[28:29]
	v_lshl_add_u64 v[52:53], v[52:53], 0, s[28:29]
	v_lshl_add_u64 v[42:43], v[42:43], 0, s[28:29]
	v_add_co_u32_e32 v62, vcc, s8, v40
	v_lshl_add_u64 v[2:3], v[2:3], 0, v[156:157]
	v_lshl_add_u64 v[4:5], v[0:1], 0, v[156:157]
	v_lshl_add_u64 v[52:53], v[52:53], 0, v[156:157]
	v_lshl_add_u64 v[42:43], v[42:43], 0, v[156:157]
	v_addc_co_u32_e32 v63, vcc, 0, v41, vcc
	s_nop 0
	global_load_dwordx4 v[64:67], v[40:41], off
	global_load_dwordx4 v[48:51], v[40:41], off offset:64
	global_load_dwordx4 v[44:47], v[40:41], off offset:128
	global_load_dwordx4 v[88:91], v[40:41], off offset:192
	global_load_dwordx4 v[100:103], v[86:87], off offset:192
	global_load_dwordx4 v[82:85], v[52:53], off
	global_load_dwordx4 v[68:71], v[60:61], off offset:-4096
	global_load_dwordx4 v[116:119], v[42:43], off
	global_load_dwordx4 v[56:59], v[62:63], off offset:64
	s_nop 0
	global_load_dwordx4 v[40:43], v[62:63], off offset:128
	global_load_dwordx4 v[72:75], v[60:61], off
	global_load_dwordx4 v[52:55], v[60:61], off offset:64
	global_load_dwordx4 v[112:115], v[60:61], off offset:128
	global_load_dwordx4 v[94:97], v[60:61], off offset:192
	global_load_dwordx4 v[104:107], v[62:63], off offset:192
	global_load_dwordx4 v[76:79], v[86:87], off
	s_nop 0
	global_load_dwordx4 v[60:63], v[86:87], off offset:64
	global_load_dwordx4 v[108:111], v[86:87], off offset:128
	s_lshl_b32 s9, s11, 10
	s_add_i32 s21, s9, 16
	s_lshl_b32 s9, s11, 13
	s_movk_i32 s24, 0x110
	s_add_i32 s1, s1, s9
	v_mul_lo_u32 v81, v177, s24
	s_add_i32 s1, s1, s0
	v_and_b32_e32 v86, 63, v176
	v_bfe_u32 v172, v176, 4, 2
	v_add3_u32 v174, 16, v81, v156
	s_add_i32 s13, s21, 0x4400
	s_add_i32 s1, s1, 0x80000
	v_lshlrev_b32_e32 v173, 3, v172
	s_waitcnt vmcnt(0)
	ds_write_b128 v174, v[82:85] offset:33792
	ds_write_b128 v174, v[116:119] offset:42496
	s_add_i32 s8, s18, 1
	v_lshl_add_u32 v81, v86, 2, s13
	v_or_b32_e32 v82, s1, v86
.LBB0_201:
	v_add_u32_e32 v84, 0xfffc0000, v82
	v_ashrrev_i32_e32 v85, 31, v84
	v_lshl_add_u64 v[84:85], v[84:85], 2, s[26:27]
	v_ashrrev_i32_e32 v83, 31, v82
	global_load_dword v236, v[84:85], off
	v_lshl_add_u64 v[84:85], v[82:83], 2, s[26:27]
	global_load_dword v237, v[84:85], off
	v_add_u32_e32 v82, 64, v82
	s_cmp_lt_u32 s8, 2
	s_cbranch_scc1 .Lsa_w
	v_add_u32_e32 v84, 0xfffc0000, v82
	v_ashrrev_i32_e32 v85, 31, v84
	v_lshl_add_u64 v[84:85], v[84:85], 2, s[26:27]
	v_ashrrev_i32_e32 v83, 31, v82
	global_load_dword v238, v[84:85], off
	v_lshl_add_u64 v[84:85], v[82:83], 2, s[26:27]
	global_load_dword v239, v[84:85], off
	v_add_u32_e32 v82, 64, v82
	s_cmp_lt_u32 s8, 3
	s_cbranch_scc1 .Lsa_w
	v_add_u32_e32 v84, 0xfffc0000, v82
	v_ashrrev_i32_e32 v85, 31, v84
	v_lshl_add_u64 v[84:85], v[84:85], 2, s[26:27]
	v_ashrrev_i32_e32 v83, 31, v82
	global_load_dword v240, v[84:85], off
	v_lshl_add_u64 v[84:85], v[82:83], 2, s[26:27]
	global_load_dword v241, v[84:85], off
	v_add_u32_e32 v82, 64, v82
	s_cmp_lt_u32 s8, 4
	s_cbranch_scc1 .Lsa_w
	v_add_u32_e32 v84, 0xfffc0000, v82
	v_ashrrev_i32_e32 v85, 31, v84
	v_lshl_add_u64 v[84:85], v[84:85], 2, s[26:27]
	v_ashrrev_i32_e32 v83, 31, v82
	global_load_dword v242, v[84:85], off
	v_lshl_add_u64 v[84:85], v[82:83], 2, s[26:27]
	global_load_dword v243, v[84:85], off
	v_add_u32_e32 v82, 64, v82
.Lsa_w:
	s_waitcnt vmcnt(0)
	ds_write2st64_b32 v81, v236, v237 offset1:32
	s_cmp_lt_u32 s8, 2
	s_cbranch_scc1 .Lsa_d
	v_add_u32_e32 v81, 0x100, v81
	ds_write2st64_b32 v81, v238, v239 offset1:32
	s_cmp_lt_u32 s8, 3
	s_cbranch_scc1 .Lsa_d
	v_add_u32_e32 v81, 0x100, v81
	ds_write2st64_b32 v81, v240, v241 offset1:32
	s_cmp_lt_u32 s8, 4
	s_cbranch_scc1 .Lsa_d
	v_add_u32_e32 v81, 0x100, v81
	ds_write2st64_b32 v81, v242, v243 offset1:32
.Lsa_d:
	global_load_dwordx4 v[0:3], v[2:3], off
	s_nop 0
	global_load_dwordx4 v[4:7], v[4:5], off
	s_nop 0
	global_load_dwordx4 v[8:11], v[32:33], off
	s_nop 0
	global_load_dwordx4 v[12:15], v[12:13], off
	s_nop 0
	global_load_dwordx4 v[16:19], v[16:17], off
	s_nop 0
	global_load_dwordx4 v[20:23], v[20:21], off
	s_nop 0
	global_load_dwordx4 v[24:27], v[24:25], off
	s_nop 0
	global_load_dwordx4 v[28:31], v[28:29], off
	s_nop 0
	global_load_dwordx4 v[32:35], v[34:35], off
	s_nop 0
	global_load_dwordx4 v[36:39], v[36:37], off
	v_lshlrev_b32_e32 v178, 1, v173
	v_mov_b32_e32 v86, 0x1100
	v_add_u32_e32 v170, 16, v178
	v_mad_u32_u24 v175, v171, s24, v86
	v_mad_u32_u24 v81, v171, s24, v170
	v_add_u32_e32 v86, v170, v175
	s_waitcnt lgkmcnt(0)
	s_barrier
	ds_read_b128 v[82:85], v81 offset:33792
	ds_read_b128 v[120:123], v86 offset:33792
	ds_read_b128 v[128:131], v86 offset:38144
	ds_read_b128 v[220:223], v86 offset:38208
	ds_read_b128 v[136:139], v86 offset:42496
	ds_read_b128 v[224:227], v86 offset:42560
	s_waitcnt lgkmcnt(5)
	v_mfma_f32_16x16x32_bf16 v[116:119], v[82:85], v[64:67], 0
	s_mov_b32 s1, s29
	s_lshl_b64 s[8:9], s[0:1], 1
	s_lshl_b32 s1, s18, 8
	s_waitcnt lgkmcnt(4)
	v_mfma_f32_16x16x32_bf16 v[124:127], v[120:123], v[64:67], 0
	s_add_i32 s1, s21, s1
	v_add_u32_e32 v156, s1, v80
	s_lshl_b32 s12, s12, 1
	s_waitcnt lgkmcnt(3)
	v_mfma_f32_16x16x32_bf16 v[132:135], v[128:131], v[64:67], 0
	s_add_u32 s22, s22, s12
	s_movk_i32 s21, 0x90
	s_addc_u32 s23, s23, 0
	s_waitcnt lgkmcnt(1)
	v_mfma_f32_16x16x32_bf16 v[64:67], v[136:139], v[64:67], 0
	s_ashr_i32 s12, s20, 3
	v_readlane_b32 s25, v253, 62
	s_and_b32 s12, s12, -16
	v_mfma_f32_16x16x32_bf16 v[140:143], v[82:85], v[68:71], 0
	s_andn2_b32 s20, s20, 63
	v_or_b32_e32 v203, 16, v171
	v_or_b32_e32 v181, 32, v171
	v_mfma_f32_16x16x32_bf16 v[144:147], v[120:123], v[68:71], 0
	v_or_b32_e32 v180, 48, v171
	s_lshl_b32 s11, s11, 1
	s_and_b32 s11, s11, 2
	v_mfma_f32_16x16x32_bf16 v[148:151], v[128:131], v[68:71], 0
	v_mul_u32_u24_e32 v179, 0x110, v171
	v_cmp_lt_u32_e64 s[38:39], v173, v171
	v_cmp_le_u32_e64 s[52:53], v173, v203
	v_mfma_f32_16x16x32_bf16 v[68:71], v[136:139], v[68:71], 0
	v_cmp_lt_u32_e64 s[54:55], v173, v203
	v_mfma_f32_16x16x32_bf16 v[152:155], v[82:85], v[72:75], 0
	v_mfma_f32_16x16x32_bf16 v[204:207], v[120:123], v[72:75], 0
	v_mfma_f32_16x16x32_bf16 v[208:211], v[128:131], v[72:75], 0
	v_mfma_f32_16x16x32_bf16 v[72:75], v[136:139], v[72:75], 0
	v_mfma_f32_16x16x32_bf16 v[82:85], v[82:85], v[76:79], 0
	v_mfma_f32_16x16x32_bf16 v[120:123], v[120:123], v[76:79], 0
	v_mfma_f32_16x16x32_bf16 v[212:215], v[128:131], v[76:79], 0
	v_mfma_f32_16x16x32_bf16 v[76:79], v[136:139], v[76:79], 0
	ds_read_b128 v[136:139], v81 offset:33856
	s_waitcnt lgkmcnt(1)
	v_mfma_f32_16x16x32_bf16 v[232:235], v[224:227], v[56:59], v[68:71]
	v_mfma_f32_16x16x32_bf16 v[68:71], v[220:223], v[60:63], v[212:215]
	s_nop 2
	ds_read_b128 v[212:215], v81 offset:33920
	s_waitcnt lgkmcnt(1)
	v_mfma_f32_16x16x32_bf16 v[216:219], v[136:139], v[48:51], v[116:119]
	s_nop 2
	ds_read_b128 v[116:119], v86 offset:33856
	s_waitcnt lgkmcnt(0)
	v_mfma_f32_16x16x32_bf16 v[124:127], v[116:119], v[48:51], v[124:127]
	v_mfma_f32_16x16x32_bf16 v[132:135], v[220:223], v[48:51], v[132:135]
	v_mfma_f32_16x16x32_bf16 v[48:51], v[224:227], v[48:51], v[64:67]
	v_mfma_f32_16x16x32_bf16 v[64:67], v[136:139], v[56:59], v[140:143]
	s_nop 2
	ds_read_b128 v[140:143], v86 offset:33920
	v_mfma_f32_16x16x32_bf16 v[228:231], v[116:119], v[56:59], v[144:147]
	v_mfma_f32_16x16x32_bf16 v[148:151], v[220:223], v[56:59], v[148:151]
	v_mfma_f32_16x16x32_bf16 v[152:155], v[136:139], v[52:55], v[152:155]
	v_mfma_f32_16x16x32_bf16 v[204:207], v[116:119], v[52:55], v[204:207]
	v_mfma_f32_16x16x32_bf16 v[144:147], v[220:223], v[52:55], v[208:211]
	v_mfma_f32_16x16x32_bf16 v[128:131], v[224:227], v[52:55], v[72:75]
	ds_read_b128 v[52:55], v81 offset:33984
	v_mfma_f32_16x16x32_bf16 v[208:211], v[136:139], v[60:63], v[82:85]
	v_mfma_f32_16x16x32_bf16 v[56:59], v[116:119], v[60:63], v[120:123]
	v_mfma_f32_16x16x32_bf16 v[116:119], v[224:227], v[60:63], v[76:79]
	s_waitcnt lgkmcnt(1)
	v_mfma_f32_16x16x32_bf16 v[60:63], v[140:143], v[44:47], v[124:127]
	s_nop 0
	ds_read_b128 v[76:79], v86 offset:38272
	s_nop 0
	ds_read_b128 v[124:127], v86 offset:42624
	v_mfma_f32_16x16x32_bf16 v[216:219], v[212:215], v[44:47], v[216:219]
	s_waitcnt lgkmcnt(1)
	v_mfma_f32_16x16x32_bf16 v[72:75], v[76:79], v[44:47], v[132:135]
	s_waitcnt lgkmcnt(0)
	v_mfma_f32_16x16x32_bf16 v[120:123], v[124:127], v[44:47], v[48:51]
	v_mfma_f32_16x16x32_bf16 v[44:47], v[212:215], v[40:43], v[64:67]
	v_mfma_f32_16x16x32_bf16 v[64:67], v[140:143], v[40:43], v[228:231]
	v_mfma_f32_16x16x32_bf16 v[82:85], v[76:79], v[40:43], v[148:151]
	v_mfma_f32_16x16x32_bf16 v[132:135], v[124:127], v[40:43], v[232:235]
	v_mfma_f32_16x16x32_bf16 v[220:223], v[212:215], v[112:115], v[152:155]
	ds_read_b128 v[40:43], v156 offset:17408
	s_nop 1
	ds_read_b128 v[152:155], v86 offset:33984
	ds_read_b128 v[148:151], v86 offset:38336
	ds_read_b128 v[136:139], v86 offset:42688
	s_waitcnt lgkmcnt(3)
	v_mul_f32_e32 v40, 0x3fb8aa3b, v40
	v_exp_f32_e32 v80, v40
	v_mul_f32_e32 v40, 0x3fb8aa3b, v41
	v_mul_f32_e32 v41, 0x3fb8aa3b, v42
	v_exp_f32_e32 v86, v41
	v_mul_f32_e32 v41, 0x3fb8aa3b, v43
	v_mfma_f32_16x16x32_bf16 v[208:211], v[212:215], v[108:111], v[208:211]
	v_exp_f32_e32 v87, v41
	v_exp_f32_e32 v81, v40
	v_mfma_f32_16x16x32_bf16 v[48:51], v[52:55], v[88:91], v[216:219]
	v_mfma_f32_16x16x32_bf16 v[44:47], v[52:55], v[104:107], v[44:47]
	v_mfma_f32_16x16x32_bf16 v[212:215], v[52:55], v[94:97], v[220:223]
	s_nop 5
	v_mul_f32_e64 v42, v50, v86
	v_mul_f32_e64 v43, v51, v87
	v_pk_mul_f32 v[50:51], v[46:47], v[86:87]
	v_pk_mul_f32 v[40:41], v[48:49], v[80:81]
	v_mfma_f32_16x16x32_bf16 v[52:55], v[52:55], v[100:103], v[208:211]
	v_mul_f32_e64 v48, v44, v80
	v_mul_f32_e64 v49, v45, v81
	v_pk_mul_f32 v[46:47], v[214:215], v[86:87]
	ds_read_b128 v[214:217], v156 offset:17472
	v_mfma_f32_16x16x32_bf16 v[204:207], v[140:143], v[112:115], v[204:207]
	v_mul_f32_e64 v44, v212, v80
	v_mul_f32_e64 v45, v213, v81
	s_nop 0
	v_pk_mul_f32 v[54:55], v[54:55], v[86:87]
	v_pk_mul_f32 v[52:53], v[52:53], v[80:81]
	v_mfma_f32_16x16x32_bf16 v[140:143], v[140:143], v[108:111], v[56:59]
	s_waitcnt lgkmcnt(0)
	v_mul_f32_e32 v80, 0x3fb8aa3b, v214
	v_mul_f32_e32 v81, 0x3fb8aa3b, v215
	v_exp_f32_e32 v80, v80
	v_mul_f32_e32 v56, 0x3fb8aa3b, v216
	v_exp_f32_e32 v86, v56
	v_mfma_f32_16x16x32_bf16 v[56:59], v[152:155], v[88:91], v[60:63]
	v_exp_f32_e32 v81, v81
	s_nop 1
	v_mul_f32_e32 v60, 0x3fb8aa3b, v217
	v_exp_f32_e32 v87, v60
	v_mfma_f32_16x16x32_bf16 v[60:63], v[152:155], v[104:107], v[64:67]
	s_nop 1
	v_mul_f32_e64 v56, v56, v80
	v_mul_f32_e64 v57, v57, v81
	v_pk_mul_f32 v[58:59], v[58:59], v[86:87]
	v_mfma_f32_16x16x32_bf16 v[64:67], v[152:155], v[94:97], v[204:207]
	s_nop 2
	ds_read_b128 v[204:207], v156 offset:17536
	v_mfma_f32_16x16x32_bf16 v[140:143], v[152:155], v[100:103], v[140:143]
	v_mul_f32_e64 v60, v60, v80
	v_mul_f32_e64 v61, v61, v81
	s_nop 0
	v_pk_mul_f32 v[64:65], v[64:65], v[80:81]
	v_pk_mul_f32 v[62:63], v[62:63], v[86:87]
	v_mfma_f32_16x16x32_bf16 v[152:155], v[76:79], v[108:111], v[68:71]
	s_waitcnt lgkmcnt(0)
	v_mul_f32_e32 v92, 0x3fb8aa3b, v204
	v_exp_f32_e32 v92, v92
	v_pk_mul_f32 v[80:81], v[140:141], v[80:81]
	v_mul_f32_e32 v68, 0x3fb8aa3b, v205
	v_mfma_f32_16x16x32_bf16 v[144:147], v[76:79], v[112:115], v[144:147]
	v_exp_f32_e32 v93, v68
	v_mul_f32_e32 v76, 0x3fb8aa3b, v206
	v_exp_f32_e32 v98, v76
	v_mfma_f32_16x16x32_bf16 v[68:71], v[148:151], v[88:91], v[72:75]
	v_mul_f32_e64 v66, v66, v86
	v_mul_f32_e64 v67, v67, v87
	s_nop 0
	v_mul_f32_e32 v72, 0x3fb8aa3b, v207
	v_exp_f32_e32 v99, v72
	v_mfma_f32_16x16x32_bf16 v[72:75], v[148:151], v[104:107], v[82:85]
	s_nop 1
	v_mul_f32_e64 v76, v68, v92
	v_mul_f32_e64 v77, v69, v93
	v_pk_mul_f32 v[78:79], v[70:71], v[98:99]
	v_pk_mul_f32 v[82:83], v[142:143], v[86:87]
	ds_read_b128 v[140:143], v156 offset:17600
	v_mfma_f32_16x16x32_bf16 v[68:71], v[148:151], v[94:97], v[144:147]
	v_mul_f32_e64 v72, v72, v92
	v_mul_f32_e64 v73, v73, v93
	v_lshlrev_b32_e32 v156, 1, v168
	v_pk_mul_f32 v[74:75], v[74:75], v[98:99]
	v_mfma_f32_16x16x32_bf16 v[84:87], v[148:151], v[100:103], v[152:155]
	v_lshl_add_u32 v150, v173, 2, 16
	s_nop 1
	v_pk_mul_f32 v[68:69], v[68:69], v[92:93]
	v_pk_mul_f32 v[70:71], v[70:71], v[98:99]
	v_mfma_f32_16x16x32_bf16 v[112:115], v[124:127], v[112:115], v[128:131]
	v_lshl_add_u32 v152, v172, 5, s13
	s_nop 0
	v_pk_mul_f32 v[84:85], v[84:85], v[92:93]
	s_waitcnt lgkmcnt(0)
	v_mul_f32_e32 v92, 0x3fb8aa3b, v140
	v_exp_f32_e32 v128, v92
	v_mul_f32_e32 v92, 0x3fb8aa3b, v141
	v_exp_f32_e32 v129, v92
	v_mfma_f32_16x16x32_bf16 v[104:107], v[136:139], v[104:107], v[132:135]
	v_mul_f32_e32 v92, 0x3fb8aa3b, v142
	v_pk_mul_f32 v[86:87], v[86:87], v[98:99]
	v_add_u32_e32 v168, v150, v179
	v_mfma_f32_16x16x32_bf16 v[108:111], v[124:127], v[108:111], v[116:119]
	v_lshlrev_b32_e32 v132, 1, v166
	v_lshl_add_u64 v[134:135], s[22:23], 0, v[156:157]
	s_nop 0
	v_exp_f32_e32 v116, v92
	v_mul_f32_e32 v92, 0x3fb8aa3b, v143
	v_exp_f32_e32 v117, v92
	v_pk_mul_f32 v[92:93], v[104:105], v[128:129]
	v_mul_lo_u32 v104, v169, s21
	v_add3_u32 v133, s25, v104, v132
	v_or_b32_e32 v104, s12, v171
	v_mfma_f32_16x16x32_bf16 v[88:91], v[136:139], v[88:91], v[120:123]
	v_lshlrev_b32_e32 v105, 2, v171
	v_add_u32_e32 v151, s1, v105
	s_lshl_b32 s1, s18, 7
	v_mfma_f32_16x16x32_bf16 v[96:99], v[136:139], v[94:97], v[112:115]
	v_mul_f32_e64 v94, v106, v116
	v_mul_f32_e64 v95, v107, v117
	v_add_u32_e32 v106, 16, v105
	v_or_b32_e32 v105, 3, v173
	v_mfma_f32_16x16x32_bf16 v[100:103], v[136:139], v[100:103], v[108:111]
	v_mad_u64_u32 v[136:137], s[22:23], v104, s24, v[170:171]
	v_lshl_or_b32 v104, v172, 2, s12
	s_nop 0
	v_or_b32_e32 v108, s20, v171
	v_mul_lo_u32 v112, v104, s24
	v_or_b32_e32 v104, 2, v173
	v_cmp_le_u32_e64 s[40:41], v104, v171
	v_cmp_le_u32_e64 s[42:43], v105, v171
	v_cmp_le_u32_e64 s[56:57], v104, v203
	v_cmp_le_u32_e64 s[58:59], v105, v203
	v_mul_lo_u32 v137, v108, s21
	v_or_b32_e32 v104, 32, v173
	v_or_b32_e32 v105, 33, v173
	v_or_b32_e32 v108, 34, v173
	v_cmp_le_u32_e64 s[68:69], v105, v181
	v_cmp_le_u32_e64 s[70:71], v108, v181
	v_cmp_le_u32_e64 s[82:83], v104, v180
	v_cmp_le_u32_e64 s[84:85], v105, v180
	v_cmp_le_u32_e64 s[86:87], v108, v180
	s_add_u32 s21, s1, 0x80
	v_add3_u32 v138, v177, s0, 64
	v_mad_i64_i32 v[104:105], s[0:1], v169, s37, 0
	v_mov_b32_e32 v108, 0x810000
	s_or_b32 s12, s11, 1
	v_mad_u64_u32 v[104:105], s[0:1], s10, v108, v[104:105]
	v_pk_mul_f32 v[90:91], v[90:91], v[116:117]
	v_pk_mul_f32 v[98:99], v[98:99], v[116:117]
	v_pk_mul_f32 v[102:103], v[102:103], v[116:117]
	v_lshl_or_b32 v109, s11, 4, v171
	v_lshl_or_b32 v110, s12, 4, v171
	v_or_b32_e32 v113, 4, v173
	v_or_b32_e32 v114, 5, v173
	v_or_b32_e32 v115, 6, v173
	v_or_b32_e32 v116, 7, v173
	v_and_b32_e32 v108, 7, v176
	s_add_u32 s0, s4, s8
	v_add_u32_e32 v107, s25, v178
	v_mul_u32_u24_e32 v109, 0x110, v109
	v_mul_u32_u24_e32 v110, 0x110, v110
	v_lshl_add_u32 v111, s11, 6, v106
	v_lshl_add_u32 v106, s12, 6, v106
	v_cmp_le_u32_e64 s[44:45], v113, v171
	v_cmp_le_u32_e64 s[46:47], v114, v171
	v_cmp_le_u32_e64 s[48:49], v115, v171
	v_cmp_le_u32_e64 s[50:51], v116, v171
	v_cmp_le_u32_e64 s[60:61], v113, v203
	v_cmp_le_u32_e64 s[62:63], v114, v203
	v_cmp_le_u32_e64 s[64:65], v115, v203
	v_cmp_le_u32_e64 s[66:67], v116, v203
	v_or_b32_e32 v113, 35, v173
	v_or_b32_e32 v114, 36, v173
	v_or_b32_e32 v115, 37, v173
	v_or_b32_e32 v116, 38, v173
	v_or_b32_e32 v117, 39, v173
	v_lshl_or_b32 v104, v108, 4, v104
	s_addc_u32 s1, s5, s9
	v_pk_mul_f32 v[88:89], v[88:89], v[128:129]
	v_pk_mul_f32 v[96:97], v[96:97], v[128:129]
	v_pk_mul_f32 v[100:101], v[100:101], v[128:129]
	v_cmp_le_u32_e64 s[24:25], v173, v171
	v_cmp_le_u32_e64 s[72:73], v113, v181
	v_cmp_le_u32_e64 s[74:75], v114, v181
	v_cmp_le_u32_e64 s[76:77], v115, v181
	v_cmp_le_u32_e64 s[78:79], v116, v181
	v_cmp_le_u32_e64 s[80:81], v117, v181
	v_cmp_le_u32_e64 s[88:89], v113, v180
	v_cmp_le_u32_e64 s[90:91], v114, v180
	v_cmp_le_u32_e64 s[92:93], v115, v180
	v_cmp_le_u32_e64 s[94:95], v116, v180
	v_cmp_le_u32_e64 s[96:97], v117, v180
	v_lshl_add_u64 v[140:141], s[0:1], 0, v[104:105]
	s_mov_b32 s22, 0
	s_mov_b64 s[8:9], 0
	v_add_u32_e32 v153, v170, v109
	v_add_u32_e32 v154, v170, v110
	v_add_u32_e32 v155, v111, v112
	v_add_u32_e32 v156, v106, v112
	v_add_u32_e32 v170, v107, v137
	s_branch .LBB0_204
